# P4 epilogue: wr0 alignment barrier moved behind the row-scale loads (plus v1 GEMM barrier tweaks)
# baseline (speedup 1.0000x reference)
; __device__ __forceinline__ unsigned pkh7(float lo, float hi) { return (pkh(lo, hi) + 0x00080008u) & 0xFFF0FFF0u; }
; #define PG8_BAR __builtin_amdgcn_s_barrier()
;     __device__ __forceinline__ void operator()(const f32x4 (&acc)[2][2][4][2], const Unit& u, int wr, int wc, int fr_, int fq_) const {
;         int t_ = threadIdx.x; asm volatile("" : "+v"(t_)); const int fr = t_ & 15, fq = (t_ >> 4) & 3;
;         const int row0 = u.pm * BM + wr * 64 + fr; const int col0 = u.pn * HALF + wc * 32 + 8 * fq;
;         float rsv[2][4];
; #pragma unroll
;         for (int ai = 0; ai < 2; ++ai)
; #pragma unroll
;             for (int m = 0; m < 4; ++m) rsv[ai][m] = rowss[row0 + ai * HALF + m * 16];
; #pragma unroll
;         for (int ai = 0; ai < 2; ++ai)
; #pragma unroll
;             for (int m = 0; m < 4; ++m) {
;                 const int row = row0 + ai * HALF + m * 16;
;                 const float rs = __builtin_amdgcn_rsqf(rsv[ai][m] * (1.0f / D) + EPS);
;                 const float nrsl = -rs * LOG2E, irs2 = rsv[ai][m] * (1.0f / D) + EPS;
;                 f32x4 hv[2];
; #pragma unroll
;                 for (int n = 0; n < 2; ++n) {
;                     const f32x4 g = acc[ai][0][m][n], up = acc[ai][1][m][n];
;                     const f32x4 a = g * nrsl; f32x4 ex;
; #pragma unroll
;                     for (int e = 0; e < 4; ++e) ex[e] = __builtin_amdgcn_exp2f(a[e]);
;                     const f32x4 dn = ex * irs2 + irs2; f32x4 rc;
; #pragma unroll
;                     for (int e = 0; e < 4; ++e) rc[e] = __builtin_amdgcn_rcpf(dn[e]);
;                     hv[n] = (g * up) * rc;
;                 }
;                 u32x4 w; w.x = pkh7(hv[0][0], hv[0][1]); w.y = pkh7(hv[0][2], hv[0][3]); w.z = pkh7(hv[1][0], hv[1][1]); w.w = pkh7(hv[1][2], hv[1][3]);
;                 *(u32x4*)(Hd + (size_t)row * DFF + col0) = w;
;     ...
;         if constexpr (ALIGN_EPI) { if (wr == 0) PG8_BAR; }
.LBB0_853:
.LBB0_855:
	s_lshl_b32 s4, s46, 8
	v_mov_b32_e32 v144, v0
	s_add_i32 s4, s4, s30
	v_pk_mul_f32 v[142:143], v[106:107], v[118:119]
	v_and_or_b32 v132, v144, 15, s4
	v_ashrrev_i32_e32 v133, 31, v132
	v_lshl_add_u64 v[134:135], v[132:133], 2, s[0:1]
	global_load_dword v150, v[134:135], off
	v_or_b32_e32 v130, 16, v132
	v_ashrrev_i32_e32 v131, 31, v130
	v_lshl_add_u64 v[136:137], v[130:131], 2, s[0:1]
	global_load_dword v131, v[136:137], off
	v_lshrrev_b32_e32 v118, 1, v144
	v_or_b32_e32 v144, 32, v132
	v_pk_mul_f32 v[140:141], v[108:109], v[120:121]
	v_or_b32_e32 v120, 48, v132
	v_ashrrev_i32_e32 v145, 31, v144
	v_ashrrev_i32_e32 v121, 31, v120
	v_lshl_add_u64 v[146:147], v[144:145], 2, s[0:1]
	v_lshl_add_u64 v[148:149], v[120:121], 2, s[0:1]
	global_load_dword v145, v[134:135], off offset:512
	global_load_dword v156, v[134:135], off offset:576
	global_load_dword v157, v[134:135], off offset:640
	s_nop 0
	global_load_dword v147, v[146:147], off
	s_nop 0
	global_load_dword v158, v[148:149], off
	global_load_dword v121, v[134:135], off offset:704
	v_pk_mul_f32 v[128:129], v[116:117], v[128:129]
	v_pk_mul_f32 v[126:127], v[114:115], v[126:127]
	v_pk_mul_f32 v[136:137], v[112:113], v[124:125]
	v_pk_mul_f32 v[138:139], v[110:111], v[122:123]
	s_lshl_b32 s4, s50, 7
	v_and_or_b32 v118, v118, 24, s4
	v_or_b32_e32 v118, s31, v118
	v_mov_b64_e32 v[122:123], s[18:19]
	v_ashrrev_i32_e32 v119, 31, v118
	v_add_u32_e32 v154, 0x80, v132
	v_add_u32_e32 v155, 0x90, v132
	v_add_u32_e32 v125, 0xa0, v132
	v_add_u32_e32 v124, 0xb0, v132
	v_mad_i64_i32 v[132:133], s[4:5], v132, s47, v[122:123]
	v_lshlrev_b64 v[118:119], 1, v[118:119]
	v_lshl_add_u64 v[132:133], v[132:133], 0, v[118:119]
	s_andn2_b64 vcc, exec, s[2:3]
	s_mov_b64 s[2:3], -1
	s_cmp_lg_u64 s[36:37], 0
	s_cbranch_scc0 .Lepi_nobar_p4
	s_barrier
.Lepi_nobar_p4:
	s_waitcnt vmcnt(7)
	v_fmamk_f32 v134, v150, 0x3a800000, v215
	v_rsq_f32_e32 v135, v134
	s_waitcnt vmcnt(6)
	v_fmamk_f32 v146, v131, 0x3a800000, v215
	v_rsq_f32_e32 v131, v146
	v_mul_f32_e32 v148, 0xbfb8aa3b, v135
	v_pk_mul_f32 v[116:117], v[116:117], v[148:149] op_sel_hi:[1,0]
	v_pk_mul_f32 v[114:115], v[114:115], v[148:149] op_sel_hi:[1,0]
	v_pk_mul_f32 v[112:113], v[112:113], v[148:149] op_sel_hi:[1,0]
	v_pk_mul_f32 v[110:111], v[110:111], v[148:149] op_sel_hi:[1,0]
	v_exp_f32_e32 v114, v114
	v_exp_f32_e32 v115, v115
	v_exp_f32_e32 v116, v116
	v_exp_f32_e32 v117, v117
	v_exp_f32_e32 v110, v110
	v_exp_f32_e32 v111, v111
	v_exp_f32_e32 v112, v112
	v_exp_f32_e32 v113, v113
	v_mul_f32_e32 v148, 0xbfb8aa3b, v131
	v_pk_mul_f32 v[108:109], v[108:109], v[148:149] op_sel_hi:[1,0]
	v_pk_mul_f32 v[106:107], v[106:107], v[148:149] op_sel_hi:[1,0]
	v_exp_f32_e32 v108, v108
	v_exp_f32_e32 v106, v106
	v_exp_f32_e32 v107, v107
	v_exp_f32_e32 v109, v109
	v_pk_fma_f32 v[116:117], v[134:135], v[116:117], v[134:135] op_sel_hi:[0,1,0]
	v_pk_fma_f32 v[114:115], v[134:135], v[114:115], v[134:135] op_sel_hi:[0,1,0]
	v_pk_fma_f32 v[112:113], v[134:135], v[112:113], v[134:135] op_sel_hi:[0,1,0]
	v_pk_fma_f32 v[110:111], v[134:135], v[110:111], v[134:135] op_sel_hi:[0,1,0]
	v_rcp_f32_e32 v114, v114
	v_rcp_f32_e32 v115, v115
	v_rcp_f32_e32 v116, v116
	v_rcp_f32_e32 v117, v117
	v_rcp_f32_e32 v110, v110
	v_rcp_f32_e32 v111, v111
	v_rcp_f32_e32 v112, v112
	v_rcp_f32_e32 v113, v113
	s_waitcnt vmcnt(2)
	v_pk_fma_f32 v[108:109], v[146:147], v[108:109], v[146:147] op_sel_hi:[0,1,0]
	v_pk_fma_f32 v[106:107], v[146:147], v[106:107], v[146:147] op_sel_hi:[0,1,0]
	v_rcp_f32_e32 v134, v106
	v_rcp_f32_e32 v135, v107
	v_rcp_f32_e32 v152, v108
	v_rcp_f32_e32 v153, v109
	v_pk_mul_f32 v[106:107], v[128:129], v[116:117]
	v_pk_mul_f32 v[108:109], v[126:127], v[114:115]
	v_pk_mul_f32 v[112:113], v[136:137], v[112:113]
	v_pk_mul_f32 v[110:111], v[138:139], v[110:111]
	v_cvt_pk_f16_f32 v108, v108, v109
	v_cvt_pk_f16_f32 v106, v106, v107
	v_cvt_pk_f16_f32 v107, v110, v111
	v_cvt_pk_f16_f32 v109, v112, v113
	v_add_u32_e32 v108, 0x80008, v108
	v_add_u32_e32 v110, 0x80008, v106
	v_add_u32_e32 v111, 0x80008, v107
	v_add_u32_e32 v109, 0x80008, v109
	v_pk_mul_f32 v[150:151], v[100:101], v[148:149] op_sel_hi:[1,0]
	v_pk_mul_f32 v[148:149], v[98:99], v[148:149] op_sel_hi:[1,0]
	v_and_b32_e32 v106, 0xfff0fff0, v108
	v_and_b32_e32 v107, 0xfff0fff0, v110
	v_and_b32_e32 v108, 0xfff0fff0, v111
	v_and_b32_e32 v109, 0xfff0fff0, v109
	v_exp_f32_e32 v148, v148
	global_store_dwordx4 v[132:133], v[106:109], off
	v_exp_f32_e32 v149, v149
	v_pk_mul_f32 v[100:101], v[100:101], v[104:105]
	v_exp_f32_e32 v106, v150
	v_exp_f32_e32 v107, v151
	v_pk_fma_f32 v[112:113], v[146:147], v[148:149], v[146:147] op_sel_hi:[0,1,0]
	v_rcp_f32_e32 v112, v112
	v_rcp_f32_e32 v113, v113
	v_pk_fma_f32 v[106:107], v[146:147], v[106:107], v[146:147] op_sel_hi:[0,1,0]
	v_rcp_f32_e32 v106, v106
	v_rcp_f32_e32 v107, v107
	v_pk_mul_f32 v[98:99], v[98:99], v[102:103]
	v_pk_mul_f32 v[108:109], v[140:141], v[152:153]
	v_pk_mul_f32 v[110:111], v[142:143], v[134:135]
	v_pk_mul_f32 v[102:103], v[100:101], v[106:107]
	v_pk_mul_f32 v[100:101], v[98:99], v[112:113]
	v_cvt_pk_f16_f32 v98, v110, v111
	v_cvt_pk_f16_f32 v100, v100, v101
	v_cvt_pk_f16_f32 v101, v102, v103
	v_fmamk_f32 v102, v147, 0x3a800000, v215
	v_rsq_f32_e32 v103, v102
	v_cvt_pk_f16_f32 v99, v108, v109
	v_add_u32_e32 v98, 0x80008, v98
	v_add_u32_e32 v99, 0x80008, v99
	v_mul_f32_e32 v106, 0xbfb8aa3b, v103
	v_pk_mul_f32 v[108:109], v[92:93], v[106:107] op_sel_hi:[1,0]
	v_pk_mul_f32 v[110:111], v[90:91], v[106:107] op_sel_hi:[1,0]
	v_pk_mul_f32 v[92:93], v[92:93], v[96:97]
	v_pk_mul_f32 v[90:91], v[90:91], v[94:95]
	v_pk_mul_f32 v[94:95], v[84:85], v[106:107] op_sel_hi:[1,0]
	v_pk_mul_f32 v[96:97], v[82:83], v[106:107] op_sel_hi:[1,0]
	v_exp_f32_e32 v94, v94
	v_exp_f32_e32 v96, v96
	v_exp_f32_e32 v95, v95
	v_exp_f32_e32 v97, v97
	v_exp_f32_e32 v110, v110
	v_exp_f32_e32 v111, v111
	v_pk_fma_f32 v[94:95], v[102:103], v[94:95], v[102:103] op_sel_hi:[0,1,0]
	v_pk_fma_f32 v[96:97], v[102:103], v[96:97], v[102:103] op_sel_hi:[0,1,0]
	v_rcp_f32_e32 v96, v96
	v_rcp_f32_e32 v94, v94
	v_rcp_f32_e32 v95, v95
	v_rcp_f32_e32 v97, v97
	v_exp_f32_e32 v108, v108
	v_exp_f32_e32 v109, v109
	v_add_u32_e32 v100, 0x80008, v100
	v_add_u32_e32 v101, 0x80008, v101
	v_mad_i64_i32 v[104:105], s[4:5], v130, s47, v[122:123]
	v_and_b32_e32 v98, 0xfff0fff0, v98
	v_and_b32_e32 v99, 0xfff0fff0, v99
	v_and_b32_e32 v100, 0xfff0fff0, v100
	v_and_b32_e32 v101, 0xfff0fff0, v101
	v_lshl_add_u64 v[104:105], v[104:105], 0, v[118:119]
	v_pk_mul_f32 v[84:85], v[84:85], v[88:89]
	v_pk_mul_f32 v[82:83], v[82:83], v[86:87]
	global_store_dwordx4 v[104:105], v[98:101], off
	v_pk_mul_f32 v[86:87], v[84:85], v[94:95]
	v_pk_mul_f32 v[84:85], v[82:83], v[96:97]
	v_pk_fma_f32 v[100:101], v[102:103], v[110:111], v[102:103] op_sel_hi:[0,1,0]
	v_pk_fma_f32 v[98:99], v[102:103], v[108:109], v[102:103] op_sel_hi:[0,1,0]
	v_rcp_f32_e32 v100, v100
	v_rcp_f32_e32 v101, v101
	v_cvt_pk_f16_f32 v84, v84, v85
	v_cvt_pk_f16_f32 v85, v86, v87
	s_waitcnt vmcnt(3)
; __device__ __forceinline__ unsigned pkh7(float lo, float hi) { return (pkh(lo, hi) + 0x00080008u) & 0xFFF0FFF0u; }
;     __device__ __forceinline__ void operator()(const f32x4 (&acc)[2][2][4][2], const Unit& u, int wr, int wc, int fr_, int fq_) const {
;     ...
;         for (int ai = 0; ai < 2; ++ai)
; #pragma unroll
;             for (int m = 0; m < 4; ++m) {
;                 const int row = row0 + ai * HALF + m * 16;
;                 const float rs = __builtin_amdgcn_rsqf(rsv[ai][m] * (1.0f / D) + EPS);
;                 const float nrsl = -rs * LOG2E, irs2 = rsv[ai][m] * (1.0f / D) + EPS;
;                 f32x4 hv[2];
; #pragma unroll
;                 for (int n = 0; n < 2; ++n) {
;                     const f32x4 g = acc[ai][0][m][n], up = acc[ai][1][m][n];
;                     const f32x4 a = g * nrsl; f32x4 ex;
; #pragma unroll
;                     for (int e = 0; e < 4; ++e) ex[e] = __builtin_amdgcn_exp2f(a[e]);
;                     const f32x4 dn = ex * irs2 + irs2; f32x4 rc;
; #pragma unroll
;                     for (int e = 0; e < 4; ++e) rc[e] = __builtin_amdgcn_rcpf(dn[e]);
;                     hv[n] = (g * up) * rc;
;                 }
;                 u32x4 w; w.x = pkh7(hv[0][0], hv[0][1]); w.y = pkh7(hv[0][2], hv[0][3]); w.z = pkh7(hv[1][0], hv[1][1]); w.w = pkh7(hv[1][2], hv[1][3]);
;                 *(u32x4*)(Hd + (size_t)row * DFF + col0) = w;
	v_fmamk_f32 v86, v158, 0x3a800000, v215
	v_rcp_f32_e32 v98, v98
	v_rcp_f32_e32 v99, v99
	v_rsq_f32_e32 v87, v86
	v_pk_mul_f32 v[90:91], v[90:91], v[100:101]
	v_add_u32_e32 v84, 0x80008, v84
	v_pk_mul_f32 v[92:93], v[92:93], v[98:99]
	v_cvt_pk_f16_f32 v82, v90, v91
	v_mul_f32_e32 v90, 0xbfb8aa3b, v87
	v_cvt_pk_f16_f32 v83, v92, v93
	v_pk_mul_f32 v[92:93], v[76:77], v[90:91] op_sel_hi:[1,0]
	v_pk_mul_f32 v[94:95], v[74:75], v[90:91] op_sel_hi:[1,0]
	v_pk_mul_f32 v[76:77], v[76:77], v[80:81]
	v_pk_mul_f32 v[74:75], v[74:75], v[78:79]
	v_pk_mul_f32 v[78:79], v[64:65], v[90:91] op_sel_hi:[1,0]
	v_pk_mul_f32 v[80:81], v[62:63], v[90:91] op_sel_hi:[1,0]
	v_exp_f32_e32 v78, v78
	v_exp_f32_e32 v80, v80
	v_exp_f32_e32 v79, v79
	v_exp_f32_e32 v81, v81
	v_exp_f32_e32 v94, v94
	v_exp_f32_e32 v95, v95
	v_pk_fma_f32 v[78:79], v[86:87], v[78:79], v[86:87] op_sel_hi:[0,1,0]
	v_pk_fma_f32 v[80:81], v[86:87], v[80:81], v[86:87] op_sel_hi:[0,1,0]
	v_rcp_f32_e32 v80, v80
	v_rcp_f32_e32 v78, v78
	v_rcp_f32_e32 v79, v79
	v_rcp_f32_e32 v81, v81
	v_exp_f32_e32 v92, v92
	v_exp_f32_e32 v93, v93
	v_add_u32_e32 v82, 0x80008, v82
	v_add_u32_e32 v83, 0x80008, v83
	v_add_u32_e32 v85, 0x80008, v85
	v_mad_i64_i32 v[88:89], s[4:5], v144, s47, v[122:123]
	v_and_b32_e32 v82, 0xfff0fff0, v82
	v_and_b32_e32 v83, 0xfff0fff0, v83
	v_and_b32_e32 v84, 0xfff0fff0, v84
	v_and_b32_e32 v85, 0xfff0fff0, v85
	v_lshl_add_u64 v[88:89], v[88:89], 0, v[118:119]
	v_pk_mul_f32 v[64:65], v[64:65], v[72:73]
	v_pk_mul_f32 v[62:63], v[62:63], v[70:71]
	global_store_dwordx4 v[88:89], v[82:85], off
	v_pk_mul_f32 v[70:71], v[64:65], v[78:79]
	v_pk_mul_f32 v[64:65], v[62:63], v[80:81]
	v_pk_fma_f32 v[84:85], v[86:87], v[94:95], v[86:87] op_sel_hi:[0,1,0]
	v_pk_fma_f32 v[82:83], v[86:87], v[92:93], v[86:87] op_sel_hi:[0,1,0]
	v_rcp_f32_e32 v84, v84
	v_rcp_f32_e32 v85, v85
	v_cvt_pk_f16_f32 v64, v64, v65
	v_cvt_pk_f16_f32 v65, v70, v71
	v_fmamk_f32 v70, v145, 0x3a800000, v215
	v_rcp_f32_e32 v82, v82
	v_rcp_f32_e32 v83, v83
	v_rsq_f32_e32 v71, v70
	v_pk_mul_f32 v[74:75], v[74:75], v[84:85]
	v_add_u32_e32 v64, 0x80008, v64
	v_pk_mul_f32 v[76:77], v[76:77], v[82:83]
	v_cvt_pk_f16_f32 v62, v74, v75
	v_mul_f32_e32 v74, 0xbfb8aa3b, v71
	v_cvt_pk_f16_f32 v63, v76, v77
	v_pk_mul_f32 v[76:77], v[60:61], v[74:75] op_sel_hi:[1,0]
	v_pk_mul_f32 v[78:79], v[58:59], v[74:75] op_sel_hi:[1,0]
	v_exp_f32_e32 v76, v76
	v_exp_f32_e32 v78, v78
	v_exp_f32_e32 v77, v77
	v_exp_f32_e32 v79, v79
	v_add_u32_e32 v62, 0x80008, v62
	v_add_u32_e32 v63, 0x80008, v63
	v_add_u32_e32 v65, 0x80008, v65
	v_mad_i64_i32 v[72:73], s[4:5], v120, s47, v[122:123]
	v_and_b32_e32 v62, 0xfff0fff0, v62
	v_and_b32_e32 v63, 0xfff0fff0, v63
	v_and_b32_e32 v64, 0xfff0fff0, v64
	v_and_b32_e32 v65, 0xfff0fff0, v65
	v_lshl_add_u64 v[72:73], v[72:73], 0, v[118:119]
	global_store_dwordx4 v[72:73], v[62:65], off
	v_pk_mul_f32 v[60:61], v[60:61], v[68:69]
	v_pk_mul_f32 v[58:59], v[58:59], v[66:67]
	v_pk_fma_f32 v[62:63], v[70:71], v[76:77], v[70:71] op_sel_hi:[0,1,0]
	v_pk_fma_f32 v[64:65], v[70:71], v[78:79], v[70:71] op_sel_hi:[0,1,0]
	v_pk_mul_f32 v[66:67], v[52:53], v[74:75] op_sel_hi:[1,0]
	v_pk_mul_f32 v[68:69], v[50:51], v[74:75] op_sel_hi:[1,0]
	v_rcp_f32_e32 v64, v64
	v_rcp_f32_e32 v65, v65
	v_rcp_f32_e32 v62, v62
	v_rcp_f32_e32 v63, v63
	v_exp_f32_e32 v68, v68
	v_exp_f32_e32 v66, v66
	v_exp_f32_e32 v67, v67
	v_exp_f32_e32 v69, v69
	v_pk_mul_f32 v[60:61], v[60:61], v[62:63]
	v_pk_mul_f32 v[58:59], v[58:59], v[64:65]
	v_pk_fma_f32 v[62:63], v[70:71], v[66:67], v[70:71] op_sel_hi:[0,1,0]
	v_pk_fma_f32 v[64:65], v[70:71], v[68:69], v[70:71] op_sel_hi:[0,1,0]
	v_rcp_f32_e32 v64, v64
	v_rcp_f32_e32 v62, v62
	v_rcp_f32_e32 v63, v63
	v_rcp_f32_e32 v65, v65
	v_pk_mul_f32 v[52:53], v[52:53], v[56:57]
	v_pk_mul_f32 v[50:51], v[50:51], v[54:55]
	v_pk_mul_f32 v[54:55], v[52:53], v[62:63]
	v_pk_mul_f32 v[52:53], v[50:51], v[64:65]
	v_cvt_pk_f16_f32 v50, v58, v59
	v_cvt_pk_f16_f32 v52, v52, v53
	v_cvt_pk_f16_f32 v53, v54, v55
	v_fmamk_f32 v54, v156, 0x3a800000, v215
	v_rsq_f32_e32 v55, v54
	v_cvt_pk_f16_f32 v51, v60, v61
	v_add_u32_e32 v50, 0x80008, v50
	v_add_u32_e32 v51, 0x80008, v51
	v_mul_f32_e32 v58, 0xbfb8aa3b, v55
	v_pk_mul_f32 v[60:61], v[44:45], v[58:59] op_sel_hi:[1,0]
	v_pk_mul_f32 v[62:63], v[42:43], v[58:59] op_sel_hi:[1,0]
	v_pk_mul_f32 v[44:45], v[44:45], v[48:49]
	v_pk_mul_f32 v[42:43], v[42:43], v[46:47]
	v_pk_mul_f32 v[46:47], v[36:37], v[58:59] op_sel_hi:[1,0]
	v_pk_mul_f32 v[48:49], v[34:35], v[58:59] op_sel_hi:[1,0]
	v_exp_f32_e32 v46, v46
	v_exp_f32_e32 v48, v48
	v_exp_f32_e32 v47, v47
	v_exp_f32_e32 v49, v49
	v_exp_f32_e32 v62, v62
	v_exp_f32_e32 v63, v63
	v_pk_fma_f32 v[46:47], v[54:55], v[46:47], v[54:55] op_sel_hi:[0,1,0]
	v_pk_fma_f32 v[48:49], v[54:55], v[48:49], v[54:55] op_sel_hi:[0,1,0]
	v_rcp_f32_e32 v48, v48
	v_rcp_f32_e32 v46, v46
	v_rcp_f32_e32 v47, v47
	v_rcp_f32_e32 v49, v49
	v_exp_f32_e32 v60, v60
	v_exp_f32_e32 v61, v61
	v_add_u32_e32 v52, 0x80008, v52
	v_add_u32_e32 v53, 0x80008, v53
	v_mad_i64_i32 v[56:57], s[4:5], v154, s47, v[122:123]
	v_and_b32_e32 v50, 0xfff0fff0, v50
	v_and_b32_e32 v51, 0xfff0fff0, v51
; __device__ __forceinline__ unsigned pkh7(float lo, float hi) { return (pkh(lo, hi) + 0x00080008u) & 0xFFF0FFF0u; }
; #define PG8_BAR __builtin_amdgcn_s_barrier()
;     __device__ __forceinline__ void operator()(const f32x4 (&acc)[2][2][4][2], const Unit& u, int wr, int wc, int fr_, int fq_) const {
;     ...
;         for (int ai = 0; ai < 2; ++ai)
; #pragma unroll
;             for (int m = 0; m < 4; ++m) {
;                 const int row = row0 + ai * HALF + m * 16;
;                 const float rs = __builtin_amdgcn_rsqf(rsv[ai][m] * (1.0f / D) + EPS);
;                 const float nrsl = -rs * LOG2E, irs2 = rsv[ai][m] * (1.0f / D) + EPS;
;                 f32x4 hv[2];
; #pragma unroll
;                 for (int n = 0; n < 2; ++n) {
;                     const f32x4 g = acc[ai][0][m][n], up = acc[ai][1][m][n];
;                     const f32x4 a = g * nrsl; f32x4 ex;
; #pragma unroll
;                     for (int e = 0; e < 4; ++e) ex[e] = __builtin_amdgcn_exp2f(a[e]);
;                     const f32x4 dn = ex * irs2 + irs2; f32x4 rc;
; #pragma unroll
;                     for (int e = 0; e < 4; ++e) rc[e] = __builtin_amdgcn_rcpf(dn[e]);
;                     hv[n] = (g * up) * rc;
;                 }
;                 u32x4 w; w.x = pkh7(hv[0][0], hv[0][1]); w.y = pkh7(hv[0][2], hv[0][3]); w.z = pkh7(hv[1][0], hv[1][1]); w.w = pkh7(hv[1][2], hv[1][3]);
;                 *(u32x4*)(Hd + (size_t)row * DFF + col0) = w;
;     ...
;         if constexpr (ALIGN_EPI) { if (wr == 1) PG8_BAR; }
	v_and_b32_e32 v52, 0xfff0fff0, v52
	v_and_b32_e32 v53, 0xfff0fff0, v53
	v_lshl_add_u64 v[56:57], v[56:57], 0, v[118:119]
	v_pk_mul_f32 v[36:37], v[36:37], v[40:41]
	v_pk_mul_f32 v[34:35], v[34:35], v[38:39]
	global_store_dwordx4 v[56:57], v[50:53], off
	v_pk_mul_f32 v[38:39], v[36:37], v[46:47]
	v_pk_mul_f32 v[36:37], v[34:35], v[48:49]
	v_pk_fma_f32 v[52:53], v[54:55], v[62:63], v[54:55] op_sel_hi:[0,1,0]
	v_pk_fma_f32 v[50:51], v[54:55], v[60:61], v[54:55] op_sel_hi:[0,1,0]
	v_rcp_f32_e32 v52, v52
	v_rcp_f32_e32 v53, v53
	v_cvt_pk_f16_f32 v36, v36, v37
	v_cvt_pk_f16_f32 v37, v38, v39
	v_fmamk_f32 v38, v157, 0x3a800000, v215
	v_rcp_f32_e32 v50, v50
	v_rcp_f32_e32 v51, v51
	v_rsq_f32_e32 v39, v38
	v_pk_mul_f32 v[42:43], v[42:43], v[52:53]
	v_add_u32_e32 v36, 0x80008, v36
	v_pk_mul_f32 v[44:45], v[44:45], v[50:51]
	v_cvt_pk_f16_f32 v34, v42, v43
	v_mul_f32_e32 v42, 0xbfb8aa3b, v39
	v_cvt_pk_f16_f32 v35, v44, v45
	v_pk_mul_f32 v[44:45], v[28:29], v[42:43] op_sel_hi:[1,0]
	v_pk_mul_f32 v[46:47], v[26:27], v[42:43] op_sel_hi:[1,0]
	v_pk_mul_f32 v[28:29], v[28:29], v[32:33]
	v_pk_mul_f32 v[26:27], v[26:27], v[30:31]
	v_pk_mul_f32 v[30:31], v[20:21], v[42:43] op_sel_hi:[1,0]
	v_pk_mul_f32 v[32:33], v[18:19], v[42:43] op_sel_hi:[1,0]
	v_exp_f32_e32 v30, v30
	v_exp_f32_e32 v32, v32
	v_exp_f32_e32 v31, v31
	v_exp_f32_e32 v33, v33
	v_exp_f32_e32 v46, v46
	v_exp_f32_e32 v47, v47
	v_pk_fma_f32 v[30:31], v[38:39], v[30:31], v[38:39] op_sel_hi:[0,1,0]
	v_pk_fma_f32 v[32:33], v[38:39], v[32:33], v[38:39] op_sel_hi:[0,1,0]
	v_rcp_f32_e32 v32, v32
	v_rcp_f32_e32 v30, v30
	v_rcp_f32_e32 v31, v31
	v_rcp_f32_e32 v33, v33
	v_exp_f32_e32 v44, v44
	v_exp_f32_e32 v45, v45
	v_add_u32_e32 v34, 0x80008, v34
	v_add_u32_e32 v35, 0x80008, v35
	v_add_u32_e32 v37, 0x80008, v37
	v_mad_i64_i32 v[40:41], s[4:5], v155, s47, v[122:123]
	v_and_b32_e32 v34, 0xfff0fff0, v34
	v_and_b32_e32 v35, 0xfff0fff0, v35
	v_and_b32_e32 v36, 0xfff0fff0, v36
	v_and_b32_e32 v37, 0xfff0fff0, v37
	v_lshl_add_u64 v[40:41], v[40:41], 0, v[118:119]
	v_pk_mul_f32 v[20:21], v[20:21], v[24:25]
	v_pk_mul_f32 v[18:19], v[18:19], v[22:23]
	global_store_dwordx4 v[40:41], v[34:37], off
	v_pk_mul_f32 v[22:23], v[20:21], v[30:31]
	v_pk_mul_f32 v[20:21], v[18:19], v[32:33]
	v_pk_fma_f32 v[36:37], v[38:39], v[46:47], v[38:39] op_sel_hi:[0,1,0]
	v_pk_fma_f32 v[34:35], v[38:39], v[44:45], v[38:39] op_sel_hi:[0,1,0]
	v_rcp_f32_e32 v36, v36
	v_rcp_f32_e32 v37, v37
	v_cvt_pk_f16_f32 v20, v20, v21
	v_cvt_pk_f16_f32 v21, v22, v23
	s_waitcnt vmcnt(6)
	v_fmamk_f32 v22, v121, 0x3a800000, v215
	v_rcp_f32_e32 v34, v34
	v_rcp_f32_e32 v35, v35
	v_rsq_f32_e32 v23, v22
	v_pk_mul_f32 v[26:27], v[26:27], v[36:37]
	v_add_u32_e32 v20, 0x80008, v20
	v_pk_mul_f32 v[28:29], v[28:29], v[34:35]
	v_cvt_pk_f16_f32 v18, v26, v27
	v_mul_f32_e32 v26, 0xbfb8aa3b, v23
	v_cvt_pk_f16_f32 v19, v28, v29
	v_pk_mul_f32 v[28:29], v[12:13], v[26:27] op_sel_hi:[1,0]
	v_pk_mul_f32 v[30:31], v[10:11], v[26:27] op_sel_hi:[1,0]
	v_pk_mul_f32 v[12:13], v[12:13], v[16:17]
	v_pk_mul_f32 v[10:11], v[10:11], v[14:15]
	v_pk_mul_f32 v[14:15], v[4:5], v[26:27] op_sel_hi:[1,0]
	v_pk_mul_f32 v[16:17], v[2:3], v[26:27] op_sel_hi:[1,0]
	v_exp_f32_e32 v30, v30
	v_exp_f32_e32 v28, v28
	v_exp_f32_e32 v29, v29
	v_exp_f32_e32 v31, v31
	v_exp_f32_e32 v16, v16
	v_exp_f32_e32 v14, v14
	v_exp_f32_e32 v15, v15
	v_exp_f32_e32 v17, v17
	v_add_u32_e32 v18, 0x80008, v18
	v_add_u32_e32 v19, 0x80008, v19
	v_add_u32_e32 v21, 0x80008, v21
	v_mad_i64_i32 v[24:25], s[4:5], v125, s47, v[122:123]
	v_and_b32_e32 v18, 0xfff0fff0, v18
	v_and_b32_e32 v19, 0xfff0fff0, v19
	v_and_b32_e32 v20, 0xfff0fff0, v20
	v_and_b32_e32 v21, 0xfff0fff0, v21
	v_lshl_add_u64 v[24:25], v[24:25], 0, v[118:119]
	global_store_dwordx4 v[24:25], v[18:21], off
	v_pk_fma_f32 v[14:15], v[22:23], v[14:15], v[22:23] op_sel_hi:[0,1,0]
	v_pk_fma_f32 v[16:17], v[22:23], v[16:17], v[22:23] op_sel_hi:[0,1,0]
	v_pk_fma_f32 v[18:19], v[22:23], v[28:29], v[22:23] op_sel_hi:[0,1,0]
	v_pk_fma_f32 v[20:21], v[22:23], v[30:31], v[22:23] op_sel_hi:[0,1,0]
	v_rcp_f32_e32 v20, v20
	v_rcp_f32_e32 v21, v21
	v_rcp_f32_e32 v18, v18
	v_rcp_f32_e32 v19, v19
	v_rcp_f32_e32 v16, v16
	v_rcp_f32_e32 v14, v14
	v_rcp_f32_e32 v15, v15
	v_rcp_f32_e32 v17, v17
	v_pk_mul_f32 v[4:5], v[4:5], v[8:9]
	v_pk_mul_f32 v[2:3], v[2:3], v[6:7]
	v_pk_mul_f32 v[12:13], v[12:13], v[18:19]
	v_pk_mul_f32 v[10:11], v[10:11], v[20:21]
	v_pk_mul_f32 v[6:7], v[4:5], v[14:15]
	v_pk_mul_f32 v[4:5], v[2:3], v[16:17]
	v_cvt_pk_f16_f32 v2, v10, v11
	v_cvt_pk_f16_f32 v3, v12, v13
	v_cvt_pk_f16_f32 v4, v4, v5
	v_cvt_pk_f16_f32 v5, v6, v7
	v_add_u32_e32 v2, 0x80008, v2
	v_add_u32_e32 v3, 0x80008, v3
	v_add_u32_e32 v4, 0x80008, v4
	v_add_u32_e32 v5, 0x80008, v5
	v_mad_i64_i32 v[6:7], s[4:5], v124, s47, v[122:123]
	v_and_b32_e32 v2, 0xfff0fff0, v2
	v_and_b32_e32 v3, 0xfff0fff0, v3
	v_and_b32_e32 v4, 0xfff0fff0, v4
	v_and_b32_e32 v5, 0xfff0fff0, v5
	v_lshl_add_u64 v[6:7], v[6:7], 0, v[118:119]
	global_store_dwordx4 v[6:7], v[2:5], off
	s_cbranch_vccnz .LBB0_838
	s_andn2_b64 vcc, exec, s[20:21]
	s_cbranch_vccnz .LBB0_837
	s_barrier
	s_branch .LBB0_837
